# v24 + inproj1 epilogue: next 16-row block's LDS staging (writes + read-back) issued right behind the current block's reads
# baseline (speedup 1.0000x reference)
; DI float siluf(float x) { return x * sigm(x); }
;   const int lane = tid & 63, wid = tid >> 6, fr = lane & 15, fq = lane >> 4;
;   float* stg = (float*)(smem + PATCH) + wid * (16 * 68);
;   asm volatile("" ::: "memory");
; #pragma unroll
;   for (int n = 0; n < 4; ++n)
; #pragma unroll
;     for (int j = 0; j < 4; ++j) stg[(fq * 4 + j) * 68 + n * 16 + fr] = am[n][j];
;   asm volatile("s_waitcnt lgkmcnt(0)" ::: "memory");
;   const float* rp = stg + (lane >> 2) * 68 + (lane & 3) * 16;
; #pragma unroll
;   for (int i = 0; i < 4; ++i) { f32x4 t = *(const f32x4*)(rp + i * 4); v[4 * i] = t[0]; v[4 * i + 1] = t[1]; v[4 * i + 2] = t[2]; v[4 * i + 3] = t[3]; }
; DI void phase_inproj1(const Params& p, int ch) {
;     ...
;     EPI256_BEGIN
;       float rs = rsqrtf(ssq1[row] * (1.f / 1024) + EPS);
; #pragma unroll
;       for (int i = 0; i < 16; ++i) { v[i] *= rs; if (isgate) v[i] = siluf(v[i]); }
;       store16_bf(Z + (size_t)row * 1024 + col, v);
;     EPI_END
.LBB0_1141:
	v_lshrrev_b32_e32 v0, 6, v157
	s_movk_i32 s0, 0x1100
	v_mul_lo_u32 v0, v0, s0
	v_add_u32_e32 v3, s33, v0
	v_lshrrev_b32_e32 v0, 2, v157
	v_and_b32_e32 v2, 15, v157
	v_and_b32_e32 v0, 12, v0
	v_lshlrev_b32_e32 v2, 2, v2
	v_mul_u32_u24_e32 v0, 0x110, v0
	v_add3_u32 v134, v3, v2, v0
	v_bfe_u32 v2, v157, 2, 4
	v_and_b32_e32 v0, 48, v158
	v_mul_u32_u24_e32 v132, 0x110, v2
	v_lshlrev_b32_e32 v133, 2, v0
	v_add3_u32 v135, v3, v132, v133
	v_ashrrev_i32_e32 v3, 1, v157
	v_and_b32_e32 v3, 0xffffff80, v3
	v_add_u32_e32 v3, s15, v3
	s_waitcnt vmcnt(0)
	s_barrier
	v_or_b32_e32 v132, v3, v2
	ds_write2_b32 v134, v128, v124 offset1:16
	ds_write2_b32 v134, v129, v125 offset0:68 offset1:84
	ds_write2_b32 v134, v130, v126 offset0:136 offset1:152
	ds_write2_b32 v134, v131, v127 offset0:204 offset1:220
	ds_write2_b32 v134, v120, v116 offset0:32 offset1:48
	ds_write2_b32 v134, v121, v117 offset0:100 offset1:116
	ds_write2_b32 v134, v122, v118 offset0:168 offset1:184
	ds_write2_b32 v134, v123, v119 offset0:236 offset1:252
	s_waitcnt lgkmcnt(0)
	v_ashrrev_i32_e32 v133, 31, v132
	ds_read_b128 v[128:131], v135
	ds_read_b128 v[124:127], v135 offset:16
	ds_read_b128 v[120:123], v135 offset:32
	ds_read_b128 v[116:119], v135 offset:48
	ds_write2_b32 v134, v112, v108 offset1:16
	ds_write2_b32 v134, v113, v109 offset0:68 offset1:84
	ds_write2_b32 v134, v114, v110 offset0:136 offset1:152
	ds_write2_b32 v134, v115, v111 offset0:204 offset1:220
	ds_write2_b32 v134, v104, v100 offset0:32 offset1:48
	ds_write2_b32 v134, v105, v101 offset0:100 offset1:116
	ds_write2_b32 v134, v106, v102 offset0:168 offset1:184
	ds_write2_b32 v134, v107, v103 offset0:236 offset1:252
	ds_read_b128 v[112:115], v135
	ds_read_b128 v[108:111], v135 offset:16
	ds_read_b128 v[104:107], v135 offset:32
	ds_read_b128 v[100:103], v135 offset:48
	v_lshl_add_u64 v[2:3], v[132:133], 2, s[78:79]
	global_load_dword v2, v[2:3], off
	s_cmpk_eq_i32 s14, 0x300
	s_cselect_b64 s[0:1], -1, 0
	s_cmpk_lg_i32 s14, 0x300
	s_waitcnt vmcnt(0)
	v_fmamk_f32 v2, v2, 0x3a800000, v148
	v_mul_f32_e32 v3, 0x4b800000, v2
	v_cmp_gt_f32_e32 vcc, s86, v2
	s_nop 1
	v_cndmask_b32_e32 v2, v2, v3, vcc
	v_rsq_f32_e32 v2, v2
	s_nop 0
	v_mul_f32_e32 v3, 0x45800000, v2
	v_cndmask_b32_e32 v136, v2, v3, vcc
	s_waitcnt lgkmcnt(15)
	v_mul_f32_e32 v2, v128, v136
	s_cbranch_scc1 .LBB0_1143
	v_mul_f32_e32 v3, 0xbfb8aa3b, v2
	v_exp_f32_e32 v3, v3
	s_nop 0
	v_add_f32_e32 v3, 1.0, v3
	v_div_scale_f32 v128, s[8:9], v3, v3, 1.0
	v_rcp_f32_e32 v137, v128
	v_div_scale_f32 v138, vcc, 1.0, v3, 1.0
	v_fma_f32 v139, -v128, v137, 1.0
	v_fmac_f32_e32 v137, v139, v137
	v_mul_f32_e32 v139, v138, v137
	v_fma_f32 v140, -v128, v139, v138
	v_fmac_f32_e32 v139, v140, v137
	v_fma_f32 v128, -v128, v139, v138
	v_div_fmas_f32 v128, v128, v137, v139
	v_div_fixup_f32 v3, v128, v3, 1.0
	v_mul_f32_e32 v2, v2, v3

; DI float siluf(float x) { return x * sigm(x); }
; DI void phase_inproj1(const Params& p, int ch) {
;     ...
;       float rs = rsqrtf(ssq1[row] * (1.f / 1024) + EPS);
; #pragma unroll
;       for (int i = 0; i < 16; ++i) { v[i] *= rs; if (isgate) v[i] = siluf(v[i]); }
.LBB0_1146:
	s_and_b64 vcc, exec, s[8:9]
	s_waitcnt lgkmcnt(14)
	v_mul_f32_e32 v124, v124, v136
	s_cbranch_vccz .LBB0_1280

; DI float siluf(float x) { return x * sigm(x); }
; DI void phase_inproj1(const Params& p, int ch) {
;     ...
;       float rs = rsqrtf(ssq1[row] * (1.f / 1024) + EPS);
; #pragma unroll
;       for (int i = 0; i < 16; ++i) { v[i] *= rs; if (isgate) v[i] = siluf(v[i]); }
.LBB0_1150:
	s_and_b64 vcc, exec, s[8:9]
	s_waitcnt lgkmcnt(13)
	v_mul_f32_e32 v120, v120, v136
	s_cbranch_vccz .LBB0_1284

; DI float siluf(float x) { return x * sigm(x); }
; DI void phase_inproj1(const Params& p, int ch) {
;     ...
;       float rs = rsqrtf(ssq1[row] * (1.f / 1024) + EPS);
; #pragma unroll
;       for (int i = 0; i < 16; ++i) { v[i] *= rs; if (isgate) v[i] = siluf(v[i]); }
.LBB0_1154:
	s_and_b64 vcc, exec, s[8:9]
	s_waitcnt lgkmcnt(12)
	v_mul_f32_e32 v130, v116, v136
	s_cbranch_vccz .LBB0_1288

; DI unsigned pack2(float a, float b) { return (unsigned)f2bf(a) | ((unsigned)f2bf(b) << 16); }
; DI float siluf(float x) { return x * sigm(x); }
; DI void store16_bf(bft* dst, const float (&v)[16]) {
;   u32x4 o0 = {pack2(v[0], v[1]), pack2(v[2], v[3]), pack2(v[4], v[5]), pack2(v[6], v[7])}, o1 = {pack2(v[8], v[9]), pack2(v[10], v[11]), pack2(v[12], v[13]), pack2(v[14], v[15])};
;   *(u32x4*)dst = o0; *(u32x4*)(dst + 8) = o1;
; }
; DI void phase_inproj1(const Params& p, int ch) {
;     ...
;       float rs = rsqrtf(ssq1[row] * (1.f / 1024) + EPS);
; #pragma unroll
;       for (int i = 0; i < 16; ++i) { v[i] *= rs; if (isgate) v[i] = siluf(v[i]); }
;       store16_bf(Z + (size_t)row * 1024 + col, v);
;     EPI_END
.LBB0_1159:
	v_and_b32_e32 v116, 0xc0, v157
	v_or3_b32 v0, v116, s14, v0
	v_lshlrev_b32_e32 v0, 1, v0
	v_lshl_add_u64 v[116:117], s[76:77], 0, v[0:1]
	v_lshlrev_b64 v[136:137], 11, v[132:133]
	v_cvt_pk_bf16_f32 v127, v126, v127
	v_cvt_pk_bf16_f32 v126, v124, v125
	v_cvt_pk_bf16_f32 v125, v128, v129
	v_cvt_pk_bf16_f32 v124, v2, v3
	v_bfe_u32 v0, v119, 16, 1
	v_bfe_u32 v3, v123, 16, 1
	v_bfe_u32 v128, v121, 16, 1
	v_add3_u32 v128, v121, v128, s27
	v_add3_u32 v3, v123, v3, s27
	v_add3_u32 v0, v119, v0, s27
	v_bfe_u32 v119, v120, 16, 1
	v_bfe_u32 v121, v122, 16, 1
	v_bfe_u32 v129, v118, 16, 1
	v_add3_u32 v118, v118, v129, s27
	v_add3_u32 v121, v122, v121, s27
	v_add3_u32 v119, v120, v119, s27
	v_lshl_add_u64 v[136:137], v[116:117], 0, v[136:137]
	v_lshrrev_b32_e32 v122, 16, v119
	v_lshrrev_b32_e32 v119, 16, v121
	v_lshrrev_b32_e32 v118, 16, v118
	v_and_or_b32 v121, v0, s71, v118
	v_cvt_pk_bf16_f32 v120, v130, v131
	v_and_or_b32 v119, v3, s71, v119
	v_and_or_b32 v118, v128, s71, v122
	global_store_dwordx4 v[136:137], v[124:127], off
	global_store_dwordx4 v[136:137], v[118:121], off offset:16
	v_or_b32_e32 v2, 16, v132
	s_waitcnt lgkmcnt(0)
	v_ashrrev_i32_e32 v3, 31, v2
	ds_write2_b32 v134, v96, v92 offset1:16
	ds_write2_b32 v134, v97, v93 offset0:68 offset1:84
	ds_write2_b32 v134, v98, v94 offset0:136 offset1:152
	ds_write2_b32 v134, v99, v95 offset0:204 offset1:220
	ds_write2_b32 v134, v88, v84 offset0:32 offset1:48
	ds_write2_b32 v134, v89, v85 offset0:100 offset1:116
	ds_write2_b32 v134, v90, v86 offset0:168 offset1:184
	ds_write2_b32 v134, v91, v87 offset0:236 offset1:252
	ds_read_b128 v[96:99], v135
	ds_read_b128 v[92:95], v135 offset:16
	ds_read_b128 v[88:91], v135 offset:32
	ds_read_b128 v[84:87], v135 offset:48
	v_lshl_add_u64 v[118:119], v[2:3], 2, s[78:79]
	global_load_dword v0, v[118:119], off
	s_waitcnt vmcnt(0)
	v_fmamk_f32 v0, v0, 0x3a800000, v148
	v_mul_f32_e32 v118, 0x4b800000, v0
	v_cmp_gt_f32_e32 vcc, s86, v0
	s_nop 1
	v_cndmask_b32_e32 v0, v0, v118, vcc
	v_rsq_f32_e32 v0, v0
	s_nop 0
	v_mul_f32_e32 v118, 0x45800000, v0
	v_cndmask_b32_e32 v118, v0, v118, vcc
	s_and_b64 vcc, exec, s[8:9]
	s_waitcnt lgkmcnt(15)
	v_mul_f32_e32 v0, v112, v118
	s_cbranch_vccz .LBB0_1291
	s_and_b64 vcc, exec, s[8:9]
	v_mul_f32_e32 v112, v113, v118
	s_cbranch_vccz .LBB0_1292

; DI float siluf(float x) { return x * sigm(x); }
; DI void phase_inproj1(const Params& p, int ch) {
;     ...
;       float rs = rsqrtf(ssq1[row] * (1.f / 1024) + EPS);
; #pragma unroll
;       for (int i = 0; i < 16; ++i) { v[i] *= rs; if (isgate) v[i] = siluf(v[i]); }
.LBB0_1163:
	s_and_b64 vcc, exec, s[8:9]
	s_waitcnt lgkmcnt(14)
	v_mul_f32_e32 v108, v108, v118
	s_cbranch_vccz .LBB0_1295

; DI float siluf(float x) { return x * sigm(x); }
; DI void phase_inproj1(const Params& p, int ch) {
;     ...
;       float rs = rsqrtf(ssq1[row] * (1.f / 1024) + EPS);
; #pragma unroll
;       for (int i = 0; i < 16; ++i) { v[i] *= rs; if (isgate) v[i] = siluf(v[i]); }
.LBB0_1167:
	s_and_b64 vcc, exec, s[8:9]
	s_waitcnt lgkmcnt(13)
	v_mul_f32_e32 v104, v104, v118
	s_cbranch_vccz .LBB0_1299

; DI float siluf(float x) { return x * sigm(x); }
; DI void phase_inproj1(const Params& p, int ch) {
;     ...
;       float rs = rsqrtf(ssq1[row] * (1.f / 1024) + EPS);
; #pragma unroll
;       for (int i = 0; i < 16; ++i) { v[i] *= rs; if (isgate) v[i] = siluf(v[i]); }
.LBB0_1171:
	s_and_b64 vcc, exec, s[8:9]
	s_waitcnt lgkmcnt(12)
	v_mul_f32_e32 v100, v100, v118
	s_cbranch_vccz .LBB0_1303

; DI unsigned pack2(float a, float b) { return (unsigned)f2bf(a) | ((unsigned)f2bf(b) << 16); }
; DI float siluf(float x) { return x * sigm(x); }
; DI void store16_bf(bft* dst, const float (&v)[16]) {
;   u32x4 o0 = {pack2(v[0], v[1]), pack2(v[2], v[3]), pack2(v[4], v[5]), pack2(v[6], v[7])}, o1 = {pack2(v[8], v[9]), pack2(v[10], v[11]), pack2(v[12], v[13]), pack2(v[14], v[15])};
;   *(u32x4*)dst = o0; *(u32x4*)(dst + 8) = o1;
; }
; DI void phase_inproj1(const Params& p, int ch) {
;     ...
;       float rs = rsqrtf(ssq1[row] * (1.f / 1024) + EPS);
; #pragma unroll
;       for (int i = 0; i < 16; ++i) { v[i] *= rs; if (isgate) v[i] = siluf(v[i]); }
;       store16_bf(Z + (size_t)row * 1024 + col, v);
;     EPI_END
.LBB0_1176:
	v_cvt_pk_bf16_f32 v111, v110, v111
	v_cvt_pk_bf16_f32 v110, v108, v109
	v_cvt_pk_bf16_f32 v109, v113, v114
	v_cvt_pk_bf16_f32 v108, v0, v112
	v_lshlrev_b64 v[2:3], 11, v[2:3]
	v_lshl_add_u64 v[2:3], v[116:117], 0, v[2:3]
	v_cvt_pk_bf16_f32 v103, v102, v103
	v_cvt_pk_bf16_f32 v102, v100, v101
	v_cvt_pk_bf16_f32 v101, v106, v107
	v_cvt_pk_bf16_f32 v100, v104, v105
	global_store_dwordx4 v[2:3], v[108:111], off
	global_store_dwordx4 v[2:3], v[100:103], off offset:16
	v_or_b32_e32 v2, 32, v132
	s_waitcnt lgkmcnt(0)
	v_ashrrev_i32_e32 v3, 31, v2
	ds_write2_b32 v134, v80, v76 offset1:16
	ds_write2_b32 v134, v81, v77 offset0:68 offset1:84
	ds_write2_b32 v134, v82, v78 offset0:136 offset1:152
	ds_write2_b32 v134, v83, v79 offset0:204 offset1:220
	ds_write2_b32 v134, v72, v68 offset0:32 offset1:48
	ds_write2_b32 v134, v73, v69 offset0:100 offset1:116
	ds_write2_b32 v134, v74, v70 offset0:168 offset1:184
	ds_write2_b32 v134, v75, v71 offset0:236 offset1:252
	ds_read_b128 v[80:83], v135
	ds_read_b128 v[76:79], v135 offset:16
	ds_read_b128 v[72:75], v135 offset:32
	ds_read_b128 v[68:71], v135 offset:48
	v_lshl_add_u64 v[100:101], v[2:3], 2, s[78:79]
	global_load_dword v0, v[100:101], off
	s_waitcnt vmcnt(0)
	v_fmamk_f32 v0, v0, 0x3a800000, v148
	v_mul_f32_e32 v100, 0x4b800000, v0
	v_cmp_gt_f32_e32 vcc, s86, v0
	s_nop 1
	v_cndmask_b32_e32 v0, v0, v100, vcc
	v_rsq_f32_e32 v0, v0
	s_nop 0
	v_mul_f32_e32 v100, 0x45800000, v0
	v_cndmask_b32_e32 v100, v0, v100, vcc
	s_and_b64 vcc, exec, s[8:9]
	s_waitcnt lgkmcnt(15)
	v_mul_f32_e32 v0, v96, v100
	s_cbranch_vccz .LBB0_1306
	s_and_b64 vcc, exec, s[8:9]
	v_mul_f32_e32 v96, v97, v100
	s_cbranch_vccz .LBB0_1307

; DI float siluf(float x) { return x * sigm(x); }
; DI void phase_inproj1(const Params& p, int ch) {
;     ...
;       float rs = rsqrtf(ssq1[row] * (1.f / 1024) + EPS);
; #pragma unroll
;       for (int i = 0; i < 16; ++i) { v[i] *= rs; if (isgate) v[i] = siluf(v[i]); }
.LBB0_1180:
	s_and_b64 vcc, exec, s[8:9]
	s_waitcnt lgkmcnt(14)
	v_mul_f32_e32 v92, v92, v100
	s_cbranch_vccz .LBB0_1310

; DI float siluf(float x) { return x * sigm(x); }
; DI void phase_inproj1(const Params& p, int ch) {
;     ...
;       float rs = rsqrtf(ssq1[row] * (1.f / 1024) + EPS);
; #pragma unroll
;       for (int i = 0; i < 16; ++i) { v[i] *= rs; if (isgate) v[i] = siluf(v[i]); }
.LBB0_1184:
	s_and_b64 vcc, exec, s[8:9]
	s_waitcnt lgkmcnt(13)
	v_mul_f32_e32 v88, v88, v100
	s_cbranch_vccz .LBB0_1314

; DI float siluf(float x) { return x * sigm(x); }
; DI void phase_inproj1(const Params& p, int ch) {
;     ...
;       float rs = rsqrtf(ssq1[row] * (1.f / 1024) + EPS);
; #pragma unroll
;       for (int i = 0; i < 16; ++i) { v[i] *= rs; if (isgate) v[i] = siluf(v[i]); }
.LBB0_1188:
	s_and_b64 vcc, exec, s[8:9]
	s_waitcnt lgkmcnt(12)
	v_mul_f32_e32 v84, v84, v100
	s_cbranch_vccz .LBB0_1318

; DI unsigned pack2(float a, float b) { return (unsigned)f2bf(a) | ((unsigned)f2bf(b) << 16); }
; DI float siluf(float x) { return x * sigm(x); }
; DI void store16_bf(bft* dst, const float (&v)[16]) {
;   u32x4 o0 = {pack2(v[0], v[1]), pack2(v[2], v[3]), pack2(v[4], v[5]), pack2(v[6], v[7])}, o1 = {pack2(v[8], v[9]), pack2(v[10], v[11]), pack2(v[12], v[13]), pack2(v[14], v[15])};
;   *(u32x4*)dst = o0; *(u32x4*)(dst + 8) = o1;
; }
; DI void phase_inproj1(const Params& p, int ch) {
;     ...
;       float rs = rsqrtf(ssq1[row] * (1.f / 1024) + EPS);
; #pragma unroll
;       for (int i = 0; i < 16; ++i) { v[i] *= rs; if (isgate) v[i] = siluf(v[i]); }
;       store16_bf(Z + (size_t)row * 1024 + col, v);
;     EPI_END
.LBB0_1193:
	v_cvt_pk_bf16_f32 v95, v94, v95
	v_cvt_pk_bf16_f32 v94, v92, v93
	v_cvt_pk_bf16_f32 v93, v97, v98
	v_cvt_pk_bf16_f32 v92, v0, v96
	v_lshlrev_b64 v[2:3], 11, v[2:3]
	v_lshl_add_u64 v[2:3], v[116:117], 0, v[2:3]
	v_cvt_pk_bf16_f32 v87, v86, v87
	v_cvt_pk_bf16_f32 v86, v84, v85
	v_cvt_pk_bf16_f32 v85, v90, v91
	v_cvt_pk_bf16_f32 v84, v88, v89
	global_store_dwordx4 v[2:3], v[92:95], off
	global_store_dwordx4 v[2:3], v[84:87], off offset:16
	v_or_b32_e32 v2, 48, v132
	s_waitcnt lgkmcnt(0)
	v_ashrrev_i32_e32 v3, 31, v2
	ds_write2_b32 v134, v64, v60 offset1:16
	ds_write2_b32 v134, v65, v61 offset0:68 offset1:84
	ds_write2_b32 v134, v66, v62 offset0:136 offset1:152
	ds_write2_b32 v134, v67, v63 offset0:204 offset1:220
	ds_write2_b32 v134, v56, v52 offset0:32 offset1:48
	ds_write2_b32 v134, v57, v53 offset0:100 offset1:116
	ds_write2_b32 v134, v58, v54 offset0:168 offset1:184
	ds_write2_b32 v134, v59, v55 offset0:236 offset1:252
	ds_read_b128 v[64:67], v135
	ds_read_b128 v[60:63], v135 offset:16
	ds_read_b128 v[56:59], v135 offset:32
	ds_read_b128 v[52:55], v135 offset:48
	v_lshl_add_u64 v[84:85], v[2:3], 2, s[78:79]
	global_load_dword v0, v[84:85], off
	s_waitcnt vmcnt(0)
	v_fmamk_f32 v0, v0, 0x3a800000, v148
	v_mul_f32_e32 v84, 0x4b800000, v0
	v_cmp_gt_f32_e32 vcc, s86, v0
	s_nop 1
	v_cndmask_b32_e32 v0, v0, v84, vcc
	v_rsq_f32_e32 v0, v0
	s_nop 0
	v_mul_f32_e32 v84, 0x45800000, v0
	v_cndmask_b32_e32 v84, v0, v84, vcc
	s_and_b64 vcc, exec, s[8:9]
	s_waitcnt lgkmcnt(15)
	v_mul_f32_e32 v0, v80, v84
	s_cbranch_vccz .LBB0_1321
	s_and_b64 vcc, exec, s[8:9]
	v_mul_f32_e32 v80, v81, v84
	s_cbranch_vccz .LBB0_1322

; DI float siluf(float x) { return x * sigm(x); }
; DI void phase_inproj1(const Params& p, int ch) {
;     ...
;       float rs = rsqrtf(ssq1[row] * (1.f / 1024) + EPS);
; #pragma unroll
;       for (int i = 0; i < 16; ++i) { v[i] *= rs; if (isgate) v[i] = siluf(v[i]); }
.LBB0_1197:
	s_and_b64 vcc, exec, s[8:9]
	s_waitcnt lgkmcnt(14)
	v_mul_f32_e32 v76, v76, v84
	s_cbranch_vccz .LBB0_1325

; DI float siluf(float x) { return x * sigm(x); }
; DI void phase_inproj1(const Params& p, int ch) {
;     ...
;       float rs = rsqrtf(ssq1[row] * (1.f / 1024) + EPS);
; #pragma unroll
;       for (int i = 0; i < 16; ++i) { v[i] *= rs; if (isgate) v[i] = siluf(v[i]); }
.LBB0_1201:
	s_and_b64 vcc, exec, s[8:9]
	s_waitcnt lgkmcnt(13)
	v_mul_f32_e32 v72, v72, v84
	s_cbranch_vccz .LBB0_1329

; DI float siluf(float x) { return x * sigm(x); }
; DI void phase_inproj1(const Params& p, int ch) {
;     ...
;       float rs = rsqrtf(ssq1[row] * (1.f / 1024) + EPS);
; #pragma unroll
;       for (int i = 0; i < 16; ++i) { v[i] *= rs; if (isgate) v[i] = siluf(v[i]); }
.LBB0_1205:
	s_and_b64 vcc, exec, s[8:9]
	s_waitcnt lgkmcnt(12)
	v_mul_f32_e32 v68, v68, v84
	s_cbranch_vccz .LBB0_1333

; DI unsigned pack2(float a, float b) { return (unsigned)f2bf(a) | ((unsigned)f2bf(b) << 16); }
; DI float siluf(float x) { return x * sigm(x); }
; DI void store16_bf(bft* dst, const float (&v)[16]) {
;   u32x4 o0 = {pack2(v[0], v[1]), pack2(v[2], v[3]), pack2(v[4], v[5]), pack2(v[6], v[7])}, o1 = {pack2(v[8], v[9]), pack2(v[10], v[11]), pack2(v[12], v[13]), pack2(v[14], v[15])};
;   *(u32x4*)dst = o0; *(u32x4*)(dst + 8) = o1;
; }
; DI void phase_inproj1(const Params& p, int ch) {
;     ...
;       float rs = rsqrtf(ssq1[row] * (1.f / 1024) + EPS);
; #pragma unroll
;       for (int i = 0; i < 16; ++i) { v[i] *= rs; if (isgate) v[i] = siluf(v[i]); }
;       store16_bf(Z + (size_t)row * 1024 + col, v);
;     EPI_END
.LBB0_1210:
	v_cvt_pk_bf16_f32 v79, v78, v79
	v_cvt_pk_bf16_f32 v78, v76, v77
	v_cvt_pk_bf16_f32 v77, v81, v82
	v_cvt_pk_bf16_f32 v76, v0, v80
	v_lshlrev_b64 v[2:3], 11, v[2:3]
	v_lshl_add_u64 v[2:3], v[116:117], 0, v[2:3]
	v_cvt_pk_bf16_f32 v71, v70, v71
	v_cvt_pk_bf16_f32 v70, v68, v69
	v_cvt_pk_bf16_f32 v69, v74, v75
	v_cvt_pk_bf16_f32 v68, v72, v73
	global_store_dwordx4 v[2:3], v[76:79], off
	global_store_dwordx4 v[2:3], v[68:71], off offset:16
	v_or_b32_e32 v2, 64, v132
	s_waitcnt lgkmcnt(0)
	v_ashrrev_i32_e32 v3, 31, v2
	ds_write2_b32 v134, v48, v44 offset1:16
	ds_write2_b32 v134, v49, v45 offset0:68 offset1:84
	ds_write2_b32 v134, v50, v46 offset0:136 offset1:152
	ds_write2_b32 v134, v51, v47 offset0:204 offset1:220
	ds_write2_b32 v134, v40, v36 offset0:32 offset1:48
	ds_write2_b32 v134, v41, v37 offset0:100 offset1:116
	ds_write2_b32 v134, v42, v38 offset0:168 offset1:184
	ds_write2_b32 v134, v43, v39 offset0:236 offset1:252
	ds_read_b128 v[48:51], v135
	ds_read_b128 v[44:47], v135 offset:16
	ds_read_b128 v[40:43], v135 offset:32
	ds_read_b128 v[36:39], v135 offset:48
	v_lshl_add_u64 v[68:69], v[2:3], 2, s[78:79]
	global_load_dword v0, v[68:69], off
	s_waitcnt vmcnt(0)
	v_fmamk_f32 v0, v0, 0x3a800000, v148
	v_mul_f32_e32 v68, 0x4b800000, v0
	v_cmp_gt_f32_e32 vcc, s86, v0
	s_nop 1
	v_cndmask_b32_e32 v0, v0, v68, vcc
	v_rsq_f32_e32 v0, v0
	s_nop 0
	v_mul_f32_e32 v68, 0x45800000, v0
	v_cndmask_b32_e32 v68, v0, v68, vcc
	s_and_b64 vcc, exec, s[8:9]
	s_waitcnt lgkmcnt(15)
	v_mul_f32_e32 v0, v64, v68
	s_cbranch_vccz .LBB0_1336
	s_and_b64 vcc, exec, s[8:9]
	v_mul_f32_e32 v64, v65, v68
	s_cbranch_vccz .LBB0_1337

; DI float siluf(float x) { return x * sigm(x); }
; DI void phase_inproj1(const Params& p, int ch) {
;     ...
;       float rs = rsqrtf(ssq1[row] * (1.f / 1024) + EPS);
; #pragma unroll
;       for (int i = 0; i < 16; ++i) { v[i] *= rs; if (isgate) v[i] = siluf(v[i]); }
.LBB0_1214:
	s_and_b64 vcc, exec, s[8:9]
	s_waitcnt lgkmcnt(14)
	v_mul_f32_e32 v60, v60, v68
	s_cbranch_vccz .LBB0_1340

; DI float siluf(float x) { return x * sigm(x); }
; DI void phase_inproj1(const Params& p, int ch) {
;     ...
;       float rs = rsqrtf(ssq1[row] * (1.f / 1024) + EPS);
; #pragma unroll
;       for (int i = 0; i < 16; ++i) { v[i] *= rs; if (isgate) v[i] = siluf(v[i]); }
.LBB0_1218:
	s_and_b64 vcc, exec, s[8:9]
	s_waitcnt lgkmcnt(13)
	v_mul_f32_e32 v56, v56, v68
	s_cbranch_vccz .LBB0_1344

; DI float siluf(float x) { return x * sigm(x); }
; DI void phase_inproj1(const Params& p, int ch) {
;     ...
;       float rs = rsqrtf(ssq1[row] * (1.f / 1024) + EPS);
; #pragma unroll
;       for (int i = 0; i < 16; ++i) { v[i] *= rs; if (isgate) v[i] = siluf(v[i]); }
.LBB0_1222:
	s_and_b64 vcc, exec, s[8:9]
	s_waitcnt lgkmcnt(12)
	v_mul_f32_e32 v52, v52, v68
	s_cbranch_vccz .LBB0_1348

; DI unsigned pack2(float a, float b) { return (unsigned)f2bf(a) | ((unsigned)f2bf(b) << 16); }
; DI float siluf(float x) { return x * sigm(x); }
; DI void store16_bf(bft* dst, const float (&v)[16]) {
;   u32x4 o0 = {pack2(v[0], v[1]), pack2(v[2], v[3]), pack2(v[4], v[5]), pack2(v[6], v[7])}, o1 = {pack2(v[8], v[9]), pack2(v[10], v[11]), pack2(v[12], v[13]), pack2(v[14], v[15])};
;   *(u32x4*)dst = o0; *(u32x4*)(dst + 8) = o1;
; }
; DI void phase_inproj1(const Params& p, int ch) {
;     ...
;       float rs = rsqrtf(ssq1[row] * (1.f / 1024) + EPS);
; #pragma unroll
;       for (int i = 0; i < 16; ++i) { v[i] *= rs; if (isgate) v[i] = siluf(v[i]); }
;       store16_bf(Z + (size_t)row * 1024 + col, v);
;     EPI_END
.LBB0_1227:
	v_cvt_pk_bf16_f32 v63, v62, v63
	v_cvt_pk_bf16_f32 v62, v60, v61
	v_cvt_pk_bf16_f32 v61, v65, v66
	v_cvt_pk_bf16_f32 v60, v0, v64
	v_lshlrev_b64 v[2:3], 11, v[2:3]
	v_lshl_add_u64 v[2:3], v[116:117], 0, v[2:3]
	v_cvt_pk_bf16_f32 v55, v54, v55
	v_cvt_pk_bf16_f32 v54, v52, v53
	v_cvt_pk_bf16_f32 v53, v58, v59
	v_cvt_pk_bf16_f32 v52, v56, v57
	global_store_dwordx4 v[2:3], v[60:63], off
	global_store_dwordx4 v[2:3], v[52:55], off offset:16
	v_or_b32_e32 v2, 0x50, v132
	s_waitcnt lgkmcnt(0)
	v_ashrrev_i32_e32 v3, 31, v2
	ds_write2_b32 v134, v32, v28 offset1:16
	ds_write2_b32 v134, v33, v29 offset0:68 offset1:84
	ds_write2_b32 v134, v34, v30 offset0:136 offset1:152
	ds_write2_b32 v134, v35, v31 offset0:204 offset1:220
	ds_write2_b32 v134, v24, v20 offset0:32 offset1:48
	ds_write2_b32 v134, v25, v21 offset0:100 offset1:116
	ds_write2_b32 v134, v26, v22 offset0:168 offset1:184
	ds_write2_b32 v134, v27, v23 offset0:236 offset1:252
	ds_read_b128 v[32:35], v135
	ds_read_b128 v[28:31], v135 offset:16
	ds_read_b128 v[24:27], v135 offset:32
	ds_read_b128 v[20:23], v135 offset:48
	v_lshl_add_u64 v[52:53], v[2:3], 2, s[78:79]
	global_load_dword v0, v[52:53], off
	s_waitcnt vmcnt(0)
	v_fmamk_f32 v0, v0, 0x3a800000, v148
	v_mul_f32_e32 v52, 0x4b800000, v0
	v_cmp_gt_f32_e32 vcc, s86, v0
	s_nop 1
	v_cndmask_b32_e32 v0, v0, v52, vcc
	v_rsq_f32_e32 v0, v0
	s_nop 0
	v_mul_f32_e32 v52, 0x45800000, v0
	v_cndmask_b32_e32 v52, v0, v52, vcc
	s_and_b64 vcc, exec, s[8:9]
	s_waitcnt lgkmcnt(15)
	v_mul_f32_e32 v0, v48, v52
	s_cbranch_vccz .LBB0_1351
	s_and_b64 vcc, exec, s[8:9]
	v_mul_f32_e32 v48, v49, v52
	s_cbranch_vccz .LBB0_1352

; DI float siluf(float x) { return x * sigm(x); }
; DI void phase_inproj1(const Params& p, int ch) {
;     ...
;       float rs = rsqrtf(ssq1[row] * (1.f / 1024) + EPS);
; #pragma unroll
;       for (int i = 0; i < 16; ++i) { v[i] *= rs; if (isgate) v[i] = siluf(v[i]); }
.LBB0_1231:
	s_and_b64 vcc, exec, s[8:9]
	s_waitcnt lgkmcnt(14)
	v_mul_f32_e32 v44, v44, v52
	s_cbranch_vccz .LBB0_1355

; DI float siluf(float x) { return x * sigm(x); }
; DI void phase_inproj1(const Params& p, int ch) {
;     ...
;       float rs = rsqrtf(ssq1[row] * (1.f / 1024) + EPS);
; #pragma unroll
;       for (int i = 0; i < 16; ++i) { v[i] *= rs; if (isgate) v[i] = siluf(v[i]); }
.LBB0_1235:
	s_and_b64 vcc, exec, s[8:9]
	s_waitcnt lgkmcnt(13)
	v_mul_f32_e32 v40, v40, v52
	s_cbranch_vccz .LBB0_1359

; DI float siluf(float x) { return x * sigm(x); }
; DI void phase_inproj1(const Params& p, int ch) {
;     ...
;       float rs = rsqrtf(ssq1[row] * (1.f / 1024) + EPS);
; #pragma unroll
;       for (int i = 0; i < 16; ++i) { v[i] *= rs; if (isgate) v[i] = siluf(v[i]); }
.LBB0_1239:
	s_and_b64 vcc, exec, s[8:9]
	s_waitcnt lgkmcnt(12)
	v_mul_f32_e32 v36, v36, v52
	s_cbranch_vccz .LBB0_1363

; DI unsigned pack2(float a, float b) { return (unsigned)f2bf(a) | ((unsigned)f2bf(b) << 16); }
; DI float siluf(float x) { return x * sigm(x); }
; DI void store16_bf(bft* dst, const float (&v)[16]) {
;   u32x4 o0 = {pack2(v[0], v[1]), pack2(v[2], v[3]), pack2(v[4], v[5]), pack2(v[6], v[7])}, o1 = {pack2(v[8], v[9]), pack2(v[10], v[11]), pack2(v[12], v[13]), pack2(v[14], v[15])};
;   *(u32x4*)dst = o0; *(u32x4*)(dst + 8) = o1;
; }
; DI void phase_inproj1(const Params& p, int ch) {
;     ...
;       float rs = rsqrtf(ssq1[row] * (1.f / 1024) + EPS);
; #pragma unroll
;       for (int i = 0; i < 16; ++i) { v[i] *= rs; if (isgate) v[i] = siluf(v[i]); }
;       store16_bf(Z + (size_t)row * 1024 + col, v);
;     EPI_END
.LBB0_1244:
	v_cvt_pk_bf16_f32 v47, v46, v47
	v_cvt_pk_bf16_f32 v46, v44, v45
	v_cvt_pk_bf16_f32 v45, v49, v50
	v_cvt_pk_bf16_f32 v44, v0, v48
	v_lshlrev_b64 v[2:3], 11, v[2:3]
	v_lshl_add_u64 v[2:3], v[116:117], 0, v[2:3]
	v_cvt_pk_bf16_f32 v39, v38, v39
	v_cvt_pk_bf16_f32 v38, v36, v37
	v_cvt_pk_bf16_f32 v37, v42, v43
	v_cvt_pk_bf16_f32 v36, v40, v41
	global_store_dwordx4 v[2:3], v[44:47], off
	global_store_dwordx4 v[2:3], v[36:39], off offset:16
	v_or_b32_e32 v2, 0x60, v132
	s_waitcnt lgkmcnt(0)
	v_ashrrev_i32_e32 v3, 31, v2
	v_lshl_add_u64 v[36:37], v[2:3], 2, s[78:79]
	global_load_dword v0, v[36:37], off
	s_waitcnt vmcnt(0)
	v_fmamk_f32 v0, v0, 0x3a800000, v148
	v_mul_f32_e32 v36, 0x4b800000, v0
	v_cmp_gt_f32_e32 vcc, s86, v0
	s_nop 1
	v_cndmask_b32_e32 v0, v0, v36, vcc
	v_rsq_f32_e32 v0, v0
	s_nop 0
	v_mul_f32_e32 v36, 0x45800000, v0
	v_cndmask_b32_e32 v36, v0, v36, vcc
	s_and_b64 vcc, exec, s[8:9]
	s_waitcnt lgkmcnt(3)
	v_mul_f32_e32 v0, v32, v36
	s_cbranch_vccz .LBB0_1366
	s_and_b64 vcc, exec, s[8:9]
	v_mul_f32_e32 v32, v33, v36
	s_cbranch_vccz .LBB0_1367

; DI float sigm(float x) { return 1.f / (1.f + __expf(-x)); }
; DI float siluf(float x) { return x * sigm(x); }
; DI void phase_inproj1(const Params& p, int ch) {
;     ...
;       for (int i = 0; i < 16; ++i) { v[i] *= rs; if (isgate) v[i] = siluf(v[i]); }
.LBB0_1279:
	v_mul_f32_e32 v130, 0xbfb8aa3b, v129
	v_exp_f32_e32 v130, v130
	s_nop 0
	v_add_f32_e32 v130, 1.0, v130
	v_rcp_f32_e32 v130, v130
	s_nop 0
	v_mul_f32_e32 v129, v129, v130
	s_and_b64 vcc, exec, s[8:9]
	s_waitcnt lgkmcnt(14)
	v_mul_f32_e32 v124, v124, v136
	s_cbranch_vccnz .LBB0_1147

; DI float sigm(float x) { return 1.f / (1.f + __expf(-x)); }
; DI float siluf(float x) { return x * sigm(x); }
; DI void phase_inproj1(const Params& p, int ch) {
;     ...
;       for (int i = 0; i < 16; ++i) { v[i] *= rs; if (isgate) v[i] = siluf(v[i]); }
.LBB0_1283:
	v_mul_f32_e32 v130, 0xbfb8aa3b, v127
	v_exp_f32_e32 v130, v130
	s_nop 0
	v_add_f32_e32 v130, 1.0, v130
	v_rcp_f32_e32 v130, v130
	s_nop 0
	v_mul_f32_e32 v127, v127, v130
	s_and_b64 vcc, exec, s[8:9]
	s_waitcnt lgkmcnt(13)
	v_mul_f32_e32 v120, v120, v136
	s_cbranch_vccnz .LBB0_1151

; DI float sigm(float x) { return 1.f / (1.f + __expf(-x)); }
; DI float siluf(float x) { return x * sigm(x); }
; DI void phase_inproj1(const Params& p, int ch) {
;     ...
;       for (int i = 0; i < 16; ++i) { v[i] *= rs; if (isgate) v[i] = siluf(v[i]); }
.LBB0_1287:
	v_mul_f32_e32 v130, 0xbfb8aa3b, v123
	v_exp_f32_e32 v130, v130
	s_nop 0
	v_add_f32_e32 v130, 1.0, v130
	v_rcp_f32_e32 v130, v130
	s_nop 0
	v_mul_f32_e32 v123, v123, v130
	s_and_b64 vcc, exec, s[8:9]
	s_waitcnt lgkmcnt(12)
	v_mul_f32_e32 v130, v116, v136
	s_cbranch_vccnz .LBB0_1155

; DI float sigm(float x) { return 1.f / (1.f + __expf(-x)); }
; DI float siluf(float x) { return x * sigm(x); }
; DI void phase_inproj1(const Params& p, int ch) {
;     ...
;       for (int i = 0; i < 16; ++i) { v[i] *= rs; if (isgate) v[i] = siluf(v[i]); }
.LBB0_1294:
	v_mul_f32_e32 v115, 0xbfb8aa3b, v114
	v_exp_f32_e32 v115, v115
	s_nop 0
	v_add_f32_e32 v115, 1.0, v115
	v_rcp_f32_e32 v115, v115
	s_nop 0
	v_mul_f32_e32 v114, v114, v115
	s_and_b64 vcc, exec, s[8:9]
	s_waitcnt lgkmcnt(14)
	v_mul_f32_e32 v108, v108, v118
	s_cbranch_vccnz .LBB0_1164

; DI float sigm(float x) { return 1.f / (1.f + __expf(-x)); }
; DI float siluf(float x) { return x * sigm(x); }
; DI void phase_inproj1(const Params& p, int ch) {
;     ...
;       for (int i = 0; i < 16; ++i) { v[i] *= rs; if (isgate) v[i] = siluf(v[i]); }
.LBB0_1298:
	v_mul_f32_e32 v115, 0xbfb8aa3b, v111
	v_exp_f32_e32 v115, v115
	s_nop 0
	v_add_f32_e32 v115, 1.0, v115
	v_rcp_f32_e32 v115, v115
	s_nop 0
	v_mul_f32_e32 v111, v111, v115
	s_and_b64 vcc, exec, s[8:9]
	s_waitcnt lgkmcnt(13)
	v_mul_f32_e32 v104, v104, v118
	s_cbranch_vccnz .LBB0_1168

; DI float sigm(float x) { return 1.f / (1.f + __expf(-x)); }
; DI float siluf(float x) { return x * sigm(x); }
; DI void phase_inproj1(const Params& p, int ch) {
;     ...
;       for (int i = 0; i < 16; ++i) { v[i] *= rs; if (isgate) v[i] = siluf(v[i]); }
.LBB0_1302:
	v_mul_f32_e32 v115, 0xbfb8aa3b, v107
	v_exp_f32_e32 v115, v115
	s_nop 0
	v_add_f32_e32 v115, 1.0, v115
	v_rcp_f32_e32 v115, v115
	s_nop 0
	v_mul_f32_e32 v107, v107, v115
	s_and_b64 vcc, exec, s[8:9]
	s_waitcnt lgkmcnt(12)
	v_mul_f32_e32 v100, v100, v118
	s_cbranch_vccnz .LBB0_1172

; DI float sigm(float x) { return 1.f / (1.f + __expf(-x)); }
; DI float siluf(float x) { return x * sigm(x); }
; DI void phase_inproj1(const Params& p, int ch) {
;     ...
;       for (int i = 0; i < 16; ++i) { v[i] *= rs; if (isgate) v[i] = siluf(v[i]); }
.LBB0_1309:
	v_mul_f32_e32 v99, 0xbfb8aa3b, v98
	v_exp_f32_e32 v99, v99
	s_nop 0
	v_add_f32_e32 v99, 1.0, v99
	v_rcp_f32_e32 v99, v99
	s_nop 0
	v_mul_f32_e32 v98, v98, v99
	s_and_b64 vcc, exec, s[8:9]
	s_waitcnt lgkmcnt(14)
	v_mul_f32_e32 v92, v92, v100
	s_cbranch_vccnz .LBB0_1181

; DI float sigm(float x) { return 1.f / (1.f + __expf(-x)); }
; DI float siluf(float x) { return x * sigm(x); }
; DI void phase_inproj1(const Params& p, int ch) {
;     ...
;       for (int i = 0; i < 16; ++i) { v[i] *= rs; if (isgate) v[i] = siluf(v[i]); }
.LBB0_1313:
	v_mul_f32_e32 v99, 0xbfb8aa3b, v95
	v_exp_f32_e32 v99, v99
	s_nop 0
	v_add_f32_e32 v99, 1.0, v99
	v_rcp_f32_e32 v99, v99
	s_nop 0
	v_mul_f32_e32 v95, v95, v99
	s_and_b64 vcc, exec, s[8:9]
	s_waitcnt lgkmcnt(13)
	v_mul_f32_e32 v88, v88, v100
	s_cbranch_vccnz .LBB0_1185

; DI float sigm(float x) { return 1.f / (1.f + __expf(-x)); }
; DI float siluf(float x) { return x * sigm(x); }
; DI void phase_inproj1(const Params& p, int ch) {
;     ...
;       for (int i = 0; i < 16; ++i) { v[i] *= rs; if (isgate) v[i] = siluf(v[i]); }
.LBB0_1317:
	v_mul_f32_e32 v99, 0xbfb8aa3b, v91
	v_exp_f32_e32 v99, v99
	s_nop 0
	v_add_f32_e32 v99, 1.0, v99
	v_rcp_f32_e32 v99, v99
	s_nop 0
	v_mul_f32_e32 v91, v91, v99
	s_and_b64 vcc, exec, s[8:9]
	s_waitcnt lgkmcnt(12)
	v_mul_f32_e32 v84, v84, v100
	s_cbranch_vccnz .LBB0_1189

; DI float sigm(float x) { return 1.f / (1.f + __expf(-x)); }
; DI float siluf(float x) { return x * sigm(x); }
; DI void phase_inproj1(const Params& p, int ch) {
;     ...
;       for (int i = 0; i < 16; ++i) { v[i] *= rs; if (isgate) v[i] = siluf(v[i]); }
.LBB0_1324:
	v_mul_f32_e32 v83, 0xbfb8aa3b, v82
	v_exp_f32_e32 v83, v83
	s_nop 0
	v_add_f32_e32 v83, 1.0, v83
	v_rcp_f32_e32 v83, v83
	s_nop 0
	v_mul_f32_e32 v82, v82, v83
	s_and_b64 vcc, exec, s[8:9]
	s_waitcnt lgkmcnt(14)
	v_mul_f32_e32 v76, v76, v84
	s_cbranch_vccnz .LBB0_1198

; DI float sigm(float x) { return 1.f / (1.f + __expf(-x)); }
; DI float siluf(float x) { return x * sigm(x); }
; DI void phase_inproj1(const Params& p, int ch) {
;     ...
;       for (int i = 0; i < 16; ++i) { v[i] *= rs; if (isgate) v[i] = siluf(v[i]); }
.LBB0_1328:
	v_mul_f32_e32 v83, 0xbfb8aa3b, v79
	v_exp_f32_e32 v83, v83
	s_nop 0
	v_add_f32_e32 v83, 1.0, v83
	v_rcp_f32_e32 v83, v83
	s_nop 0
	v_mul_f32_e32 v79, v79, v83
	s_and_b64 vcc, exec, s[8:9]
	s_waitcnt lgkmcnt(13)
	v_mul_f32_e32 v72, v72, v84
	s_cbranch_vccnz .LBB0_1202

; DI float sigm(float x) { return 1.f / (1.f + __expf(-x)); }
; DI float siluf(float x) { return x * sigm(x); }
; DI void phase_inproj1(const Params& p, int ch) {
;     ...
;       for (int i = 0; i < 16; ++i) { v[i] *= rs; if (isgate) v[i] = siluf(v[i]); }
.LBB0_1332:
	v_mul_f32_e32 v83, 0xbfb8aa3b, v75
	v_exp_f32_e32 v83, v83
	s_nop 0
	v_add_f32_e32 v83, 1.0, v83
	v_rcp_f32_e32 v83, v83
	s_nop 0
	v_mul_f32_e32 v75, v75, v83
	s_and_b64 vcc, exec, s[8:9]
	s_waitcnt lgkmcnt(12)
	v_mul_f32_e32 v68, v68, v84
	s_cbranch_vccnz .LBB0_1206

; DI float sigm(float x) { return 1.f / (1.f + __expf(-x)); }
; DI float siluf(float x) { return x * sigm(x); }
; DI void phase_inproj1(const Params& p, int ch) {
;     ...
;       for (int i = 0; i < 16; ++i) { v[i] *= rs; if (isgate) v[i] = siluf(v[i]); }
.LBB0_1339:
	v_mul_f32_e32 v67, 0xbfb8aa3b, v66
	v_exp_f32_e32 v67, v67
	s_nop 0
	v_add_f32_e32 v67, 1.0, v67
	v_rcp_f32_e32 v67, v67
	s_nop 0
	v_mul_f32_e32 v66, v66, v67
	s_and_b64 vcc, exec, s[8:9]
	s_waitcnt lgkmcnt(14)
	v_mul_f32_e32 v60, v60, v68
	s_cbranch_vccnz .LBB0_1215

; DI float sigm(float x) { return 1.f / (1.f + __expf(-x)); }
; DI float siluf(float x) { return x * sigm(x); }
; DI void phase_inproj1(const Params& p, int ch) {
;     ...
;       for (int i = 0; i < 16; ++i) { v[i] *= rs; if (isgate) v[i] = siluf(v[i]); }
.LBB0_1343:
	v_mul_f32_e32 v67, 0xbfb8aa3b, v63
	v_exp_f32_e32 v67, v67
	s_nop 0
	v_add_f32_e32 v67, 1.0, v67
	v_rcp_f32_e32 v67, v67
	s_nop 0
	v_mul_f32_e32 v63, v63, v67
	s_and_b64 vcc, exec, s[8:9]
	s_waitcnt lgkmcnt(13)
	v_mul_f32_e32 v56, v56, v68
	s_cbranch_vccnz .LBB0_1219

; DI float sigm(float x) { return 1.f / (1.f + __expf(-x)); }
; DI float siluf(float x) { return x * sigm(x); }
; DI void phase_inproj1(const Params& p, int ch) {
;     ...
;       for (int i = 0; i < 16; ++i) { v[i] *= rs; if (isgate) v[i] = siluf(v[i]); }
.LBB0_1347:
	v_mul_f32_e32 v67, 0xbfb8aa3b, v59
	v_exp_f32_e32 v67, v67
	s_nop 0
	v_add_f32_e32 v67, 1.0, v67
	v_rcp_f32_e32 v67, v67
	s_nop 0
	v_mul_f32_e32 v59, v59, v67
	s_and_b64 vcc, exec, s[8:9]
	s_waitcnt lgkmcnt(12)
	v_mul_f32_e32 v52, v52, v68
	s_cbranch_vccnz .LBB0_1223

; DI float sigm(float x) { return 1.f / (1.f + __expf(-x)); }
; DI float siluf(float x) { return x * sigm(x); }
; DI void phase_inproj1(const Params& p, int ch) {
;     ...
;       for (int i = 0; i < 16; ++i) { v[i] *= rs; if (isgate) v[i] = siluf(v[i]); }
.LBB0_1354:
	v_mul_f32_e32 v51, 0xbfb8aa3b, v50
	v_exp_f32_e32 v51, v51
	s_nop 0
	v_add_f32_e32 v51, 1.0, v51
	v_rcp_f32_e32 v51, v51
	s_nop 0
	v_mul_f32_e32 v50, v50, v51
	s_and_b64 vcc, exec, s[8:9]
	s_waitcnt lgkmcnt(14)
	v_mul_f32_e32 v44, v44, v52
	s_cbranch_vccnz .LBB0_1232

; DI float sigm(float x) { return 1.f / (1.f + __expf(-x)); }
; DI float siluf(float x) { return x * sigm(x); }
; DI void phase_inproj1(const Params& p, int ch) {
;     ...
;       for (int i = 0; i < 16; ++i) { v[i] *= rs; if (isgate) v[i] = siluf(v[i]); }
.LBB0_1358:
	v_mul_f32_e32 v51, 0xbfb8aa3b, v47
	v_exp_f32_e32 v51, v51
	s_nop 0
	v_add_f32_e32 v51, 1.0, v51
	v_rcp_f32_e32 v51, v51
	s_nop 0
	v_mul_f32_e32 v47, v47, v51
	s_and_b64 vcc, exec, s[8:9]
	s_waitcnt lgkmcnt(13)
	v_mul_f32_e32 v40, v40, v52
	s_cbranch_vccnz .LBB0_1236

; DI float sigm(float x) { return 1.f / (1.f + __expf(-x)); }
; DI float siluf(float x) { return x * sigm(x); }
; DI void phase_inproj1(const Params& p, int ch) {
;     ...
;       for (int i = 0; i < 16; ++i) { v[i] *= rs; if (isgate) v[i] = siluf(v[i]); }
.LBB0_1362:
	v_mul_f32_e32 v51, 0xbfb8aa3b, v43
	v_exp_f32_e32 v51, v51
	s_nop 0
	v_add_f32_e32 v51, 1.0, v51
	v_rcp_f32_e32 v51, v51
	s_nop 0
	v_mul_f32_e32 v43, v43, v51
	s_and_b64 vcc, exec, s[8:9]
	s_waitcnt lgkmcnt(12)
	v_mul_f32_e32 v36, v36, v52
	s_cbranch_vccnz .LBB0_1240
